# v33 + state-copy loop: load wait deferred to just before each store (store address arithmetic overlaps the load)
# speedup vs baseline: 1.0026x; 1.0026x over previous
.LBB0_1391:
	v_mov_b32_e32 v0, v4
	v_add_u32_e32 v4, 0x10000, v0
	v_mul_hi_i32 v2, v4, s4
	v_add_u32_e32 v2, v2, v4
	v_lshrrev_b32_e32 v3, 31, v2
	v_ashrrev_i32_e32 v2, 12, v2
	v_add_u32_e32 v7, v2, v3
	v_mad_i32_i24 v8, v7, s5, v0
	v_add_u32_e32 v2, 0x10000, v8
	v_lshl_or_b32 v3, v7, 11, v5
	v_lshl_add_u32 v9, v7, 3, v6
	v_cmp_gt_i32_e32 vcc, s21, v4
	v_cmp_lt_i32_e64 s[6:7], s20, v4
	s_nop 0
	v_cndmask_b32_e32 v3, v9, v3, vcc
	v_cmp_lt_i32_e32 vcc, s22, v2
	s_and_saveexec_b64 s[16:17], vcc
	s_xor_b64 s[16:17], exec, s[16:17]
	s_cbranch_execz .LBB0_1397
	v_add_u32_e32 v0, 0xee00, v8
	v_mov_b64_e32 v[8:9], s[10:11]
	v_mad_i64_i32 v[2:3], s[18:19], v3, s23, v[8:9]
	v_lshl_add_u64 v[2:3], v[0:1], 1, v[2:3]
	v_add_co_u32_e32 v2, vcc, 0x1000, v2
	s_nop 1
	v_addc_co_u32_e32 v3, vcc, 0, v3, vcc
	global_load_ushort v2, v[2:3], off offset:1024
	s_and_saveexec_b64 s[18:19], s[6:7]
	s_xor_b64 s[18:19], exec, s[18:19]
	s_cbranch_execz .LBB0_1394
	v_add_u32_e32 v3, -8, v7
	v_mov_b64_e32 v[8:9], s[8:9]
	v_mad_u64_u32 v[8:9], s[30:31], v3, s24, v[8:9]
	v_lshl_add_u64 v[8:9], v[0:1], 2, v[8:9]
	v_add_co_u32_e32 v8, vcc, 0xac7e000, v8
	s_nop 1
	v_addc_co_u32_e32 v9, vcc, 0, v9, vcc
	s_waitcnt vmcnt(0)
	v_lshlrev_b32_e32 v2, 16, v2
	global_store_dword v[8:9], v2, off
.LBB0_1394:
	s_andn2_saveexec_b64 s[18:19], s[18:19]
	s_cbranch_execz .LBB0_1396
	v_mul_i32_i24_e32 v8, 0xd00, v7
	v_ashrrev_i32_e32 v9, 31, v8
	v_lshl_add_u64 v[8:9], v[8:9], 2, s[8:9]
	v_lshl_add_u64 v[8:9], v[0:1], 2, v[8:9]
	v_add_co_u32_e32 v8, vcc, 0x4a24000, v8
	s_nop 1
	v_addc_co_u32_e32 v9, vcc, 0, v9, vcc
	s_waitcnt vmcnt(0)
	v_lshlrev_b32_e32 v2, 16, v2
	global_store_dword v[8:9], v2, off

.LBB0_1397:
	s_andn2_saveexec_b64 s[16:17], s[16:17]
	s_cbranch_execz .LBB0_1390
	v_mul_hi_i32 v9, v2, s25
	v_lshrrev_b32_e32 v10, 31, v9
	v_ashrrev_i32_e32 v9, 8, v9
	v_mul_i32_i24_e32 v8, 0xffffe100, v7
	v_add_u32_e32 v9, v9, v10
	v_mad_i32_i24 v8, v9, s26, v8
	v_add3_u32 v8, v0, v8, s3
	v_add3_u32 v0, v3, v9, -2
	v_mov_b64_e32 v[10:11], s[10:11]
	v_ashrrev_i32_e32 v9, 31, v8
	v_mad_i64_i32 v[10:11], s[18:19], v0, s23, v[10:11]
	v_lshl_add_u64 v[8:9], v[8:9], 1, v[10:11]
	global_load_ushort v0, v[8:9], off offset:2048
	v_ashrrev_i32_e32 v3, 31, v2
	s_and_saveexec_b64 s[18:19], s[6:7]
	s_xor_b64 s[6:7], exec, s[18:19]
	s_cbranch_execz .LBB0_1400
	v_add_u32_e32 v7, -8, v7
	v_mov_b64_e32 v[8:9], s[8:9]
	v_mad_u64_u32 v[8:9], s[18:19], v7, s27, v[8:9]
	v_lshl_add_u64 v[2:3], v[2:3], 2, v[8:9]
	v_add_co_u32_e32 v2, vcc, 0x8a3e000, v2
	s_nop 1
	v_addc_co_u32_e32 v3, vcc, 0, v3, vcc
	s_waitcnt vmcnt(0)
	v_lshlrev_b32_e32 v0, 16, v0
	global_store_dword v[2:3], v0, off
.LBB0_1400:
	s_andn2_saveexec_b64 s[6:7], s[6:7]
	s_cbranch_execz .LBB0_1389
	v_mul_i32_i24_e32 v7, 3, v7
	v_mov_b64_e32 v[8:9], s[8:9]
	v_mad_i64_i32 v[8:9], s[18:19], v7, s28, v[8:9]
	v_lshl_add_u64 v[2:3], v[2:3], 2, v[8:9]
	v_add_co_u32_e32 v2, vcc, 0x4800000, v2
	s_nop 1
	v_addc_co_u32_e32 v3, vcc, 0, v3, vcc
	s_waitcnt vmcnt(0)
	v_lshlrev_b32_e32 v0, 16, v0
	global_store_dword v[2:3], v0, off
	s_branch .LBB0_1389
